# DIFF attention unit epilogue: 16 g_diff_out slice loads hoisted into distinct quads and waited once (was load + vmcnt(0) per slice)
# baseline (speedup 1.0000x reference)
.LBB0_580:
	s_waitcnt lgkmcnt(0)
	s_barrier
	s_cmpk_gt_u32 s90, 0xff
	s_cbranch_scc1 .LBB0_582
	ds_read2st64_b32 v[68:69], v67 offset1:1
	ds_read2st64_b32 v[70:71], v67 offset0:2 offset1:3
	ds_read2st64_b32 v[72:73], v67 offset0:4 offset1:5
	ds_read2st64_b32 v[74:75], v67 offset0:6 offset1:7
	v_mov_b32_e32 v184, v48
	s_mov_b32 s0, 0xf800000
	s_mov_b32 s4, 0x3f4ccccd
	s_waitcnt lgkmcnt(0)
	v_mov_b32_e32 v65, v68
	v_pk_mul_f32 v[76:77], v[184:185], v[64:65]
	v_mov_b32_e32 v184, v49
	v_mov_b32_e32 v65, v69
	v_pk_mul_f32 v[68:69], v[184:185], v[64:65]
	v_mov_b32_e32 v184, v50
	v_mov_b32_e32 v65, v70
	v_sub_f32_e32 v49, v68, v69
	v_pk_mul_f32 v[68:69], v[184:185], v[64:65]
	v_mov_b32_e32 v184, v51
	v_mov_b32_e32 v65, v71
	v_sub_f32_e32 v50, v68, v69
	v_pk_mul_f32 v[68:69], v[184:185], v[64:65]
	v_mov_b32_e32 v184, v52
	v_mov_b32_e32 v65, v72
	v_sub_f32_e32 v66, v68, v69
	v_pk_mul_f32 v[68:69], v[184:185], v[64:65]
	v_mov_b32_e32 v184, v53
	v_mov_b32_e32 v65, v73
	v_pk_mul_f32 v[52:53], v[184:185], v[64:65]
	v_mov_b32_e32 v184, v54
	v_mov_b32_e32 v65, v74
	v_sub_f32_e32 v51, v68, v69
	v_pk_mul_f32 v[68:69], v[184:185], v[64:65]
	v_sub_f32_e32 v52, v52, v53
	v_sub_f32_e32 v53, v68, v69
	ds_read2st64_b32 v[68:69], v67 offset0:8 offset1:9
	v_mov_b32_e32 v184, v55
	v_mov_b32_e32 v65, v75
	ds_read2st64_b32 v[70:71], v67 offset0:10 offset1:11
	ds_read2st64_b32 v[72:73], v67 offset0:12 offset1:13
	ds_read2st64_b32 v[74:75], v67 offset0:14 offset1:15
	v_pk_mul_f32 v[54:55], v[184:185], v[64:65]
	v_mov_b32_e32 v184, v56
	s_waitcnt lgkmcnt(0)
	v_mov_b32_e32 v65, v68
	v_sub_f32_e32 v48, v76, v77
	v_pk_mul_f32 v[76:77], v[184:185], v[64:65]
	v_mov_b32_e32 v184, v57
	v_mov_b32_e32 v65, v69
	v_pk_mul_f32 v[56:57], v[184:185], v[64:65]
	v_mov_b32_e32 v184, v58
	v_mov_b32_e32 v65, v70
	v_pk_mul_f32 v[68:69], v[184:185], v[64:65]
	v_mov_b32_e32 v184, v59
	v_mov_b32_e32 v65, v71
	v_pk_mul_f32 v[58:59], v[184:185], v[64:65]
	v_mov_b32_e32 v184, v60
	v_mov_b32_e32 v65, v72
	v_sub_f32_e32 v56, v56, v57
	v_sub_f32_e32 v57, v68, v69
	v_pk_mul_f32 v[68:69], v[184:185], v[64:65]
	v_mov_b32_e32 v184, v61
	v_mov_b32_e32 v65, v73
	v_pk_mul_f32 v[60:61], v[184:185], v[64:65]
	v_mov_b32_e32 v184, v62
	v_mov_b32_e32 v65, v74
	v_sub_f32_e32 v58, v58, v59
	v_sub_f32_e32 v59, v68, v69
	v_pk_mul_f32 v[68:69], v[184:185], v[64:65]
	v_sub_f32_e32 v60, v60, v61
	v_sub_f32_e32 v61, v68, v69
	ds_read2st64_b32 v[68:69], v67 offset0:16 offset1:17
	v_mov_b32_e32 v184, v63
	v_mov_b32_e32 v65, v75
	ds_read2st64_b32 v[70:71], v67 offset0:18 offset1:19
	ds_read2st64_b32 v[72:73], v67 offset0:20 offset1:21
	ds_read2st64_b32 v[74:75], v67 offset0:22 offset1:23
	v_pk_mul_f32 v[62:63], v[184:185], v[64:65]
	v_mov_b32_e32 v184, v32
	s_waitcnt lgkmcnt(0)
	v_mov_b32_e32 v65, v68
	v_sub_f32_e32 v54, v54, v55
	v_sub_f32_e32 v55, v76, v77
	v_pk_mul_f32 v[76:77], v[184:185], v[64:65]
	v_mov_b32_e32 v184, v33
	v_mov_b32_e32 v65, v69
	v_pk_mul_f32 v[68:69], v[184:185], v[64:65]
	v_mov_b32_e32 v184, v34
	v_mov_b32_e32 v65, v70
	v_sub_f32_e32 v62, v62, v63
	v_sub_f32_e32 v63, v68, v69
	v_pk_mul_f32 v[68:69], v[184:185], v[64:65]
	v_mov_b32_e32 v184, v35
	v_mov_b32_e32 v65, v71
	v_sub_f32_e32 v34, v68, v69
	v_pk_mul_f32 v[68:69], v[184:185], v[64:65]
	v_mov_b32_e32 v184, v36
	v_mov_b32_e32 v65, v72
	v_pk_mul_f32 v[70:71], v[184:185], v[64:65]
	v_mov_b32_e32 v184, v37
	v_mov_b32_e32 v65, v73
	v_pk_mul_f32 v[36:37], v[184:185], v[64:65]
	v_mov_b32_e32 v184, v38
	v_mov_b32_e32 v65, v74
	v_sub_f32_e32 v35, v36, v37
	v_pk_mul_f32 v[36:37], v[184:185], v[64:65]
	v_mov_b32_e32 v184, v39
	v_mov_b32_e32 v65, v75
	v_pk_mul_f32 v[38:39], v[184:185], v[64:65]
	v_sub_f32_e32 v36, v36, v37
	v_sub_f32_e32 v37, v38, v39
	ds_read2st64_b32 v[38:39], v67 offset0:24 offset1:25
	v_sub_f32_e32 v33, v70, v71
	ds_read2st64_b32 v[70:71], v67 offset0:26 offset1:27
	ds_read2st64_b32 v[72:73], v67 offset0:28 offset1:29
	ds_read2st64_b32 v[74:75], v67 offset0:30 offset1:31
	v_mov_b32_e32 v184, v40
	v_sub_f32_e32 v32, v76, v77
	s_waitcnt lgkmcnt(0)
	v_mov_b32_e32 v65, v38
	v_pk_mul_f32 v[76:77], v[184:185], v[64:65]
	v_mov_b32_e32 v184, v41
	v_mov_b32_e32 v65, v39
	v_pk_mul_f32 v[40:41], v[184:185], v[64:65]
	v_mov_b32_e32 v184, v42
	v_mov_b32_e32 v65, v70
	v_sub_f32_e32 v38, v76, v77
	v_pk_mul_f32 v[76:77], v[184:185], v[64:65]
	v_mov_b32_e32 v184, v43
	v_mov_b32_e32 v65, v71
	v_pk_mul_f32 v[42:43], v[184:185], v[64:65]
	v_mov_b32_e32 v184, v44
	v_mov_b32_e32 v65, v72
	v_pk_mul_f32 v[70:71], v[184:185], v[64:65]
	v_mov_b32_e32 v184, v45
	v_mov_b32_e32 v65, v73
	v_pk_mul_f32 v[44:45], v[184:185], v[64:65]
	v_mov_b32_e32 v184, v46
	v_mov_b32_e32 v65, v74
	v_sub_f32_e32 v43, v42, v43
	v_sub_f32_e32 v42, v44, v45
	v_pk_mul_f32 v[44:45], v[184:185], v[64:65]
	v_mov_b32_e32 v184, v47
	v_mov_b32_e32 v65, v75
	v_pk_mul_f32 v[46:47], v[184:185], v[64:65]
	v_sub_f32_e32 v44, v44, v45
	v_sub_f32_e32 v45, v46, v47
	ds_read2st64_b32 v[46:47], v67 offset0:32 offset1:33
	v_sub_f32_e32 v39, v70, v71
	ds_read2st64_b32 v[70:71], v67 offset0:34 offset1:35
	ds_read2st64_b32 v[72:73], v67 offset0:36 offset1:37
	ds_read2st64_b32 v[74:75], v67 offset0:38 offset1:39
	v_mov_b32_e32 v184, v16
	v_sub_f32_e32 v40, v40, v41
	s_waitcnt lgkmcnt(0)
	v_mov_b32_e32 v65, v46
	v_sub_f32_e32 v41, v76, v77
	v_pk_mul_f32 v[76:77], v[184:185], v[64:65]
	v_mov_b32_e32 v184, v17
	v_mov_b32_e32 v65, v47
	v_pk_mul_f32 v[46:47], v[184:185], v[64:65]
	v_mov_b32_e32 v184, v18
	v_mov_b32_e32 v65, v70
	v_sub_f32_e32 v16, v76, v77
	v_pk_mul_f32 v[76:77], v[184:185], v[64:65]
	v_mov_b32_e32 v184, v19
	v_mov_b32_e32 v65, v71
	v_pk_mul_f32 v[70:71], v[184:185], v[64:65]
	v_mov_b32_e32 v184, v20
	v_mov_b32_e32 v65, v72
	v_sub_f32_e32 v46, v46, v47
	v_sub_f32_e32 v47, v70, v71
	v_pk_mul_f32 v[70:71], v[184:185], v[64:65]
	v_mov_b32_e32 v184, v21
	v_mov_b32_e32 v65, v73
	v_pk_mul_f32 v[20:21], v[184:185], v[64:65]
	v_mov_b32_e32 v184, v22
	v_mov_b32_e32 v65, v74
	v_sub_f32_e32 v19, v20, v21
	v_pk_mul_f32 v[20:21], v[184:185], v[64:65]
	v_mov_b32_e32 v184, v23
	v_mov_b32_e32 v65, v75
	v_pk_mul_f32 v[22:23], v[184:185], v[64:65]
	v_sub_f32_e32 v20, v20, v21
	v_sub_f32_e32 v21, v22, v23
	ds_read2st64_b32 v[22:23], v67 offset0:40 offset1:41
	v_sub_f32_e32 v17, v70, v71
	ds_read2st64_b32 v[70:71], v67 offset0:42 offset1:43
	ds_read2st64_b32 v[72:73], v67 offset0:44 offset1:45
	ds_read2st64_b32 v[74:75], v67 offset0:46 offset1:47
	v_mov_b32_e32 v184, v24
	v_sub_f32_e32 v18, v76, v77
	s_waitcnt lgkmcnt(0)
	v_mov_b32_e32 v65, v22
	v_pk_mul_f32 v[76:77], v[184:185], v[64:65]
	v_mov_b32_e32 v184, v25
	v_mov_b32_e32 v65, v23
	v_pk_mul_f32 v[24:25], v[184:185], v[64:65]
	v_mov_b32_e32 v184, v26
	v_mov_b32_e32 v65, v70
	v_sub_f32_e32 v22, v76, v77
	v_pk_mul_f32 v[76:77], v[184:185], v[64:65]
	v_mov_b32_e32 v184, v27
	v_mov_b32_e32 v65, v71
	v_pk_mul_f32 v[26:27], v[184:185], v[64:65]
	v_mov_b32_e32 v184, v28
	v_mov_b32_e32 v65, v72
	v_pk_mul_f32 v[70:71], v[184:185], v[64:65]
	v_mov_b32_e32 v184, v29
	v_mov_b32_e32 v65, v73
	v_pk_mul_f32 v[28:29], v[184:185], v[64:65]
	v_mov_b32_e32 v184, v30
	v_mov_b32_e32 v65, v74
	v_sub_f32_e32 v27, v26, v27
	v_sub_f32_e32 v26, v28, v29
	v_pk_mul_f32 v[28:29], v[184:185], v[64:65]
	v_mov_b32_e32 v184, v31
	v_mov_b32_e32 v65, v75
	v_pk_mul_f32 v[30:31], v[184:185], v[64:65]
	v_sub_f32_e32 v28, v28, v29
	v_sub_f32_e32 v29, v30, v31
	ds_read2st64_b32 v[30:31], v67 offset0:48 offset1:49
	v_sub_f32_e32 v24, v24, v25
	v_sub_f32_e32 v25, v76, v77
	v_sub_f32_e32 v23, v70, v71
	ds_read2st64_b32 v[70:71], v67 offset0:50 offset1:51
	ds_read2st64_b32 v[74:75], v67 offset0:52 offset1:53
	ds_read2st64_b32 v[76:77], v67 offset0:54 offset1:55
	v_mov_b32_e32 v184, v0
	s_waitcnt lgkmcnt(0)
	v_mov_b32_e32 v65, v30
	v_pk_mul_f32 v[72:73], v[184:185], v[64:65]
	v_mov_b32_e32 v184, v1
	v_mov_b32_e32 v65, v31
	v_pk_mul_f32 v[0:1], v[184:185], v[64:65]
	v_mov_b32_e32 v184, v2
	v_mov_b32_e32 v65, v70
	v_sub_f32_e32 v68, v68, v69
	v_sub_f32_e32 v69, v0, v1
	v_pk_mul_f32 v[0:1], v[184:185], v[64:65]
	v_mov_b32_e32 v184, v3
	v_mov_b32_e32 v65, v71
	v_sub_f32_e32 v70, v0, v1
	v_pk_mul_f32 v[0:1], v[184:185], v[64:65]
	v_mov_b32_e32 v184, v4
	v_mov_b32_e32 v65, v74
	v_sub_f32_e32 v30, v72, v73
	v_sub_f32_e32 v72, v0, v1
	v_pk_mul_f32 v[0:1], v[184:185], v[64:65]
	v_mov_b32_e32 v184, v5
	v_mov_b32_e32 v65, v75
	v_sub_f32_e32 v31, v0, v1
	v_pk_mul_f32 v[0:1], v[184:185], v[64:65]
	v_mov_b32_e32 v184, v6
	v_mov_b32_e32 v65, v76
	v_sub_f32_e32 v71, v0, v1
	v_pk_mul_f32 v[0:1], v[184:185], v[64:65]
	v_mov_b32_e32 v184, v7
	v_mov_b32_e32 v65, v77
	v_sub_f32_e32 v6, v0, v1
	v_pk_mul_f32 v[0:1], v[184:185], v[64:65]
	v_mov_b32_e32 v184, v8
	v_sub_f32_e32 v7, v0, v1
	ds_read2st64_b32 v[0:1], v67 offset0:56 offset1:57
	ds_read2st64_b32 v[2:3], v67 offset0:58 offset1:59
	ds_read2st64_b32 v[4:5], v67 offset0:60 offset1:61
	ds_read2st64_b32 v[74:75], v67 offset0:62 offset1:63
	v_mul_f32_e32 v67, v48, v48
	v_fmac_f32_e32 v67, v49, v49
	v_fmac_f32_e32 v67, v50, v50
	v_fmac_f32_e32 v67, v66, v66
	v_fmac_f32_e32 v67, v51, v51
	v_fmac_f32_e32 v67, v52, v52
	v_fmac_f32_e32 v67, v53, v53
	v_fmac_f32_e32 v67, v54, v54
	v_fmac_f32_e32 v67, v55, v55
	v_fmac_f32_e32 v67, v56, v56
	v_fmac_f32_e32 v67, v57, v57
	v_fmac_f32_e32 v67, v58, v58
	v_fmac_f32_e32 v67, v59, v59
	v_fmac_f32_e32 v67, v60, v60
	s_waitcnt lgkmcnt(0)
	v_mov_b32_e32 v65, v0
	v_fmac_f32_e32 v67, v61, v61
	v_pk_mul_f32 v[76:77], v[184:185], v[64:65]
	v_mov_b32_e32 v184, v9
	v_mov_b32_e32 v65, v1
	v_fmac_f32_e32 v67, v62, v62
	v_pk_mul_f32 v[0:1], v[184:185], v[64:65]
	v_mov_b32_e32 v184, v10
	v_mov_b32_e32 v65, v2
	v_fmac_f32_e32 v67, v32, v32
	v_sub_f32_e32 v9, v0, v1
	v_pk_mul_f32 v[0:1], v[184:185], v[64:65]
	v_mov_b32_e32 v184, v11
	v_mov_b32_e32 v65, v3
	v_fmac_f32_e32 v67, v63, v63
	v_sub_f32_e32 v10, v0, v1
	v_pk_mul_f32 v[0:1], v[184:185], v[64:65]
	v_fmac_f32_e32 v67, v34, v34
	v_sub_f32_e32 v11, v0, v1
	v_pk_mul_f32 v[0:1], v[186:187], v[4:5]
	v_pk_mul_f32 v[2:3], v[186:187], v[74:75]
	v_fmac_f32_e32 v67, v68, v68
	v_pk_fma_f32 v[0:1], v[12:13], v[64:65], v[0:1] op_sel_hi:[1,0,1] neg_lo:[0,0,1] neg_hi:[0,0,1]
	v_pk_fma_f32 v[2:3], v[14:15], v[64:65], v[2:3] op_sel_hi:[1,0,1] neg_lo:[0,0,1] neg_hi:[0,0,1]
	v_fmac_f32_e32 v67, v33, v33
	global_load_dwordx4 v[12:15], v[114:115], off
	global_load_dwordx4 v[80:83], v[114:115], off offset:32
	global_load_dwordx4 v[84:87], v[114:115], off offset:64
	global_load_dwordx4 v[88:91], v[114:115], off offset:96
	global_load_dwordx4 v[92:95], v[114:115], off offset:128
	global_load_dwordx4 v[96:99], v[114:115], off offset:160
	global_load_dwordx4 v[100:103], v[114:115], off offset:192
	global_load_dwordx4 v[104:107], v[114:115], off offset:224
	global_load_dwordx4 v[124:127], v[114:115], off offset:256
	global_load_dwordx4 v[128:131], v[114:115], off offset:288
	global_load_dwordx4 v[132:135], v[114:115], off offset:320
	global_load_dwordx4 v[136:139], v[114:115], off offset:352
	global_load_dwordx4 v[140:143], v[114:115], off offset:384
	global_load_dwordx4 v[144:147], v[114:115], off offset:416
	global_load_dwordx4 v[148:151], v[114:115], off offset:448
	global_load_dwordx4 v[168:171], v[114:115], off offset:480
	v_fmac_f32_e32 v67, v35, v35
	v_fmac_f32_e32 v67, v36, v36
	v_fmac_f32_e32 v67, v37, v37
	v_fmac_f32_e32 v67, v38, v38
	v_fmac_f32_e32 v67, v40, v40
	v_fmac_f32_e32 v67, v41, v41
	v_fmac_f32_e32 v67, v43, v43
	v_fmac_f32_e32 v67, v39, v39
	v_fmac_f32_e32 v67, v42, v42
	v_fmac_f32_e32 v67, v44, v44
	v_fmac_f32_e32 v67, v45, v45
	v_fmac_f32_e32 v67, v16, v16
	v_fmac_f32_e32 v67, v46, v46
	v_fmac_f32_e32 v67, v18, v18
	v_fmac_f32_e32 v67, v47, v47
	v_fmac_f32_e32 v67, v17, v17
	v_fmac_f32_e32 v67, v19, v19
	v_fmac_f32_e32 v67, v20, v20
	v_fmac_f32_e32 v67, v21, v21
	v_fmac_f32_e32 v67, v22, v22
	v_fmac_f32_e32 v67, v24, v24
	v_fmac_f32_e32 v67, v25, v25
	v_fmac_f32_e32 v67, v27, v27
	v_fmac_f32_e32 v67, v23, v23
	v_fmac_f32_e32 v67, v26, v26
	v_fmac_f32_e32 v67, v28, v28
	v_fmac_f32_e32 v67, v29, v29
	v_fmac_f32_e32 v67, v30, v30
	v_fmac_f32_e32 v67, v69, v69
	v_fmac_f32_e32 v67, v70, v70
	v_fmac_f32_e32 v67, v72, v72
	v_fmac_f32_e32 v67, v31, v31
	v_fmac_f32_e32 v67, v71, v71
	v_fmac_f32_e32 v67, v6, v6
	v_sub_f32_e32 v8, v76, v77
	v_fmac_f32_e32 v67, v7, v7
	v_fmac_f32_e32 v67, v8, v8
	v_fmac_f32_e32 v67, v9, v9
	v_fmac_f32_e32 v67, v10, v10
	v_pk_mul_f32 v[4:5], v[0:1], v[0:1]
	v_fmac_f32_e32 v67, v11, v11
	v_add_f32_e32 v4, v67, v4
	v_pk_mul_f32 v[64:65], v[2:3], v[2:3]
	v_add_f32_e32 v4, v4, v5
	v_add_f32_e32 v4, v4, v64
	v_add_f32_e32 v4, v4, v65
	ds_bpermute_b32 v5, v197, v4
	s_waitcnt lgkmcnt(0)
	v_add_f32_e32 v4, v4, v5
	v_fmamk_f32 v4, v4, 0x3c000000, v206
	v_mul_f32_e32 v5, 0x4f800000, v4
	v_cmp_gt_f32_e32 vcc, s0, v4
	s_nop 1
	v_cndmask_b32_e32 v4, v4, v5, vcc
	v_sqrt_f32_e32 v5, v4
	s_nop 0
	v_add_u32_e32 v64, -1, v5
	v_fma_f32 v65, -v64, v5, v4
	v_cmp_ge_f32_e64 s[0:1], 0, v65
	v_add_u32_e32 v65, 1, v5
	s_nop 0
	v_cndmask_b32_e64 v64, v5, v64, s[0:1]
	v_fma_f32 v5, -v65, v5, v4
	v_cmp_lt_f32_e64 s[0:1], 0, v5
	s_nop 1
	v_cndmask_b32_e64 v5, v64, v65, s[0:1]
	v_mul_f32_e32 v64, 0x37800000, v5
	v_cndmask_b32_e32 v5, v5, v64, vcc
	v_cmp_class_f32_e32 vcc, v4, v207
	s_nop 1
	v_cndmask_b32_e32 v4, v5, v4, vcc
	v_div_scale_f32 v5, s[0:1], v4, v4, s4
	v_rcp_f32_e32 v64, v5
	v_readlane_b32 s0, v249, 46
	v_readlane_b32 s1, v249, 47
	v_fma_f32 v65, -v5, v64, 1.0
	v_fmac_f32_e32 v64, v65, v64
	v_div_scale_f32 v65, vcc, s4, v4, s4
	v_mul_f32_e32 v67, v65, v64
	v_fma_f32 v73, -v5, v67, v65
	v_fmac_f32_e32 v67, v73, v64
	v_fma_f32 v5, -v5, v67, v65
	v_div_fmas_f32 v5, v5, v64, v67
	v_div_fixup_f32 v64, v5, v4, s4
	v_mul_f32_e32 v4, v48, v64
	v_mul_f32_e32 v5, v49, v64
	s_waitcnt vmcnt(0)
	v_mul_f32_e32 v4, v12, v4
	v_mul_f32_e32 v5, v13, v5
	v_cvt_pk_bf16_f32 v48, v4, v5
	v_mul_f32_e32 v4, v50, v64
	v_mul_f32_e32 v5, v66, v64
	v_mul_f32_e32 v4, v14, v4
	v_mul_f32_e32 v5, v15, v5
	v_cvt_pk_bf16_f32 v49, v4, v5
	v_mul_f32_e32 v50, v51, v64
	v_lshlrev_b64 v[4:5], 11, v[188:189]
	v_lshl_add_u64 v[4:5], s[0:1], 0, v[4:5]
	v_lshl_add_u64 v[4:5], v[4:5], 0, s[94:95]
	v_lshl_add_u64 v[4:5], v[4:5], 0, v[112:113]
	v_mul_f32_e32 v32, v32, v64
	v_mul_f32_e32 v34, v34, v64
	v_mul_f32_e32 v33, v33, v64
	v_mul_f32_e32 v35, v35, v64
	v_mul_f32_e32 v36, v36, v64
	v_mul_f32_e32 v37, v37, v64
	v_mul_f32_e32 v16, v16, v64
	v_mul_f32_e32 v18, v18, v64
	v_mul_f32_e32 v17, v17, v64
	v_mul_f32_e32 v19, v19, v64
	v_mul_f32_e32 v20, v20, v64
	v_mul_f32_e32 v21, v21, v64
	v_mul_f32_e32 v6, v6, v64
	v_mul_f32_e32 v7, v7, v64
	v_mul_f32_e32 v0, v0, v64
	v_mul_f32_e32 v1, v1, v64
	v_mul_f32_e32 v2, v2, v64
	v_mul_f32_e32 v3, v3, v64
	v_mul_f32_e32 v12, v80, v50
	v_mul_f32_e32 v50, v52, v64
	v_mul_f32_e32 v13, v81, v50
	v_cvt_pk_bf16_f32 v12, v12, v13
	v_mul_f32_e32 v13, v53, v64
	v_mul_f32_e32 v13, v82, v13
	v_mul_f32_e32 v14, v54, v64
	v_mul_f32_e32 v14, v83, v14
	v_cvt_pk_bf16_f32 v13, v13, v14
	v_cndmask_b32_e64 v14, v48, v12, s[2:3]
	ds_bpermute_b32 v15, v197, v14
	v_cndmask_b32_e64 v14, v49, v13, s[2:3]
	ds_bpermute_b32 v50, v197, v14
	s_waitcnt lgkmcnt(1)
	v_cndmask_b32_e64 v14, v12, v15, s[2:3]
	v_cndmask_b32_e64 v12, v15, v48, s[2:3]
	s_waitcnt lgkmcnt(0)
	v_cndmask_b32_e64 v15, v13, v50, s[2:3]
	v_cndmask_b32_e64 v13, v50, v49, s[2:3]
	global_store_dwordx4 v[4:5], v[12:15], off
	v_mul_f32_e32 v48, v55, v64
	v_mul_f32_e32 v50, v59, v64
	v_mul_f32_e32 v12, v48, v84
	v_mul_f32_e32 v48, v56, v64
	v_mul_f32_e32 v13, v48, v85
	v_cvt_pk_bf16_f32 v48, v12, v13
	v_mul_f32_e32 v12, v57, v64
	v_mul_f32_e32 v13, v58, v64
	v_mul_f32_e32 v12, v12, v86
	v_mul_f32_e32 v13, v13, v87
	v_cvt_pk_bf16_f32 v49, v12, v13
	v_mul_f32_e32 v12, v50, v88
	v_mul_f32_e32 v50, v60, v64
	v_mul_f32_e32 v13, v50, v89
	v_cvt_pk_bf16_f32 v12, v12, v13
	v_mul_f32_e32 v13, v61, v64
	v_mul_f32_e32 v13, v13, v90
	v_mul_f32_e32 v14, v62, v64
	v_mul_f32_e32 v14, v14, v91
	v_cvt_pk_bf16_f32 v13, v13, v14
	v_cndmask_b32_e64 v14, v48, v12, s[2:3]
	ds_bpermute_b32 v15, v197, v14
	v_cndmask_b32_e64 v14, v49, v13, s[2:3]
	ds_bpermute_b32 v50, v197, v14
	s_waitcnt lgkmcnt(1)
	v_cndmask_b32_e64 v14, v12, v15, s[2:3]
	v_cndmask_b32_e64 v12, v15, v48, s[2:3]
	s_waitcnt lgkmcnt(0)
	v_cndmask_b32_e64 v15, v13, v50, s[2:3]
	v_cndmask_b32_e64 v13, v50, v49, s[2:3]
	global_store_dwordx4 v[4:5], v[12:15], off offset:32
	v_mul_f32_e32 v48, v63, v64
	v_mul_f32_e32 v49, v68, v64
	v_mul_f32_e32 v12, v32, v92
	v_mul_f32_e32 v13, v48, v93
	v_mul_f32_e32 v14, v34, v94
	v_cvt_pk_bf16_f32 v32, v12, v13
	v_mul_f32_e32 v12, v49, v95
	v_cvt_pk_bf16_f32 v34, v14, v12
	v_mul_f32_e32 v12, v33, v96
	v_mul_f32_e32 v13, v35, v97
	v_mul_f32_e32 v14, v36, v98
	v_mul_f32_e32 v15, v37, v99
	v_cvt_pk_bf16_f32 v12, v12, v13
	v_cvt_pk_bf16_f32 v13, v14, v15
	v_mul_f32_e32 v35, v43, v64
	v_cndmask_b32_e64 v14, v32, v12, s[2:3]
	ds_bpermute_b32 v15, v197, v14
	v_cndmask_b32_e64 v14, v34, v13, s[2:3]
	ds_bpermute_b32 v33, v197, v14
	v_mul_f32_e32 v36, v44, v64
	v_mul_f32_e32 v37, v45, v64
	s_waitcnt lgkmcnt(1)
	v_cndmask_b32_e64 v14, v12, v15, s[2:3]
	v_cndmask_b32_e64 v12, v15, v32, s[2:3]
	s_waitcnt lgkmcnt(0)
	v_cndmask_b32_e64 v15, v13, v33, s[2:3]
	v_cndmask_b32_e64 v13, v33, v34, s[2:3]
	global_store_dwordx4 v[4:5], v[12:15], off offset:64
	v_mul_f32_e32 v32, v38, v64
	v_mul_f32_e32 v33, v40, v64
	v_mul_f32_e32 v34, v41, v64
	v_mul_f32_e32 v12, v32, v100
	v_mul_f32_e32 v13, v33, v101
	v_mul_f32_e32 v14, v34, v102
	v_mul_f32_e32 v15, v35, v103
	v_cvt_pk_bf16_f32 v32, v12, v13
	v_cvt_pk_bf16_f32 v33, v14, v15
	v_mul_f32_e32 v34, v39, v64
	v_mul_f32_e32 v35, v42, v64
	v_mul_f32_e32 v12, v34, v104
	v_mul_f32_e32 v13, v35, v105
	v_mul_f32_e32 v14, v36, v106
	v_mul_f32_e32 v15, v37, v107
	v_cvt_pk_bf16_f32 v12, v12, v13
	v_cvt_pk_bf16_f32 v13, v14, v15
	s_nop 0
	v_cndmask_b32_e64 v14, v32, v12, s[2:3]
	ds_bpermute_b32 v15, v197, v14
	v_cndmask_b32_e64 v14, v33, v13, s[2:3]
	ds_bpermute_b32 v34, v197, v14
	s_waitcnt lgkmcnt(1)
	v_cndmask_b32_e64 v14, v12, v15, s[2:3]
	v_cndmask_b32_e64 v12, v15, v32, s[2:3]
	s_waitcnt lgkmcnt(0)
	v_cndmask_b32_e64 v15, v13, v34, s[2:3]
	v_cndmask_b32_e64 v13, v34, v33, s[2:3]
	global_store_dwordx4 v[4:5], v[12:15], off offset:96
	v_mul_f32_e32 v32, v46, v64
	v_mul_f32_e32 v33, v47, v64
	v_mul_f32_e32 v12, v16, v124
	v_mul_f32_e32 v13, v32, v125
	v_mul_f32_e32 v14, v18, v126
	v_mul_f32_e32 v15, v33, v127
	v_cvt_pk_bf16_f32 v16, v12, v13
	v_cvt_pk_bf16_f32 v18, v14, v15
	v_mul_f32_e32 v12, v17, v128
	v_mul_f32_e32 v13, v19, v129
	v_mul_f32_e32 v14, v20, v130
	v_mul_f32_e32 v15, v21, v131
	v_cvt_pk_bf16_f32 v12, v12, v13
	v_cvt_pk_bf16_f32 v13, v14, v15
	v_mul_f32_e32 v19, v27, v64
	v_cndmask_b32_e64 v14, v16, v12, s[2:3]
	ds_bpermute_b32 v15, v197, v14
	v_cndmask_b32_e64 v14, v18, v13, s[2:3]
	ds_bpermute_b32 v17, v197, v14
	v_mul_f32_e32 v20, v28, v64
	v_mul_f32_e32 v21, v29, v64
	s_waitcnt lgkmcnt(1)
	v_cndmask_b32_e64 v14, v12, v15, s[2:3]
	v_cndmask_b32_e64 v12, v15, v16, s[2:3]
	s_waitcnt lgkmcnt(0)
	v_cndmask_b32_e64 v15, v13, v17, s[2:3]
	v_cndmask_b32_e64 v13, v17, v18, s[2:3]
	global_store_dwordx4 v[4:5], v[12:15], off offset:128
	v_mul_f32_e32 v16, v22, v64
	v_mul_f32_e32 v17, v24, v64
	v_mul_f32_e32 v18, v25, v64
	v_mul_f32_e32 v12, v16, v132
	v_mul_f32_e32 v13, v17, v133
	v_mul_f32_e32 v14, v18, v134
	v_mul_f32_e32 v15, v19, v135
	v_cvt_pk_bf16_f32 v16, v12, v13
	v_cvt_pk_bf16_f32 v17, v14, v15
	v_mul_f32_e32 v18, v23, v64
	v_mul_f32_e32 v19, v26, v64
	v_mul_f32_e32 v12, v18, v136
	v_mul_f32_e32 v13, v19, v137
	v_mul_f32_e32 v14, v20, v138
	v_mul_f32_e32 v15, v21, v139
	v_cvt_pk_bf16_f32 v12, v12, v13
	v_cvt_pk_bf16_f32 v13, v14, v15
	v_mul_f32_e32 v19, v72, v64
	v_cndmask_b32_e64 v14, v16, v12, s[2:3]
	ds_bpermute_b32 v15, v197, v14
	v_cndmask_b32_e64 v14, v17, v13, s[2:3]
	ds_bpermute_b32 v18, v197, v14
	s_waitcnt lgkmcnt(1)
	v_cndmask_b32_e64 v14, v12, v15, s[2:3]
	v_cndmask_b32_e64 v12, v15, v16, s[2:3]
	s_waitcnt lgkmcnt(0)
	v_cndmask_b32_e64 v15, v13, v18, s[2:3]
	v_cndmask_b32_e64 v13, v18, v17, s[2:3]
	global_store_dwordx4 v[4:5], v[12:15], off offset:160
	v_mul_f32_e32 v16, v30, v64
	v_mul_f32_e32 v17, v69, v64
	v_mul_f32_e32 v18, v70, v64
	v_mul_f32_e32 v12, v16, v140
	v_mul_f32_e32 v13, v17, v141
	v_mul_f32_e32 v14, v18, v142
	v_mul_f32_e32 v15, v19, v143
	v_cvt_pk_bf16_f32 v16, v12, v13
	v_cvt_pk_bf16_f32 v17, v14, v15
	v_mul_f32_e32 v18, v31, v64
	v_mul_f32_e32 v19, v71, v64
	v_mul_f32_e32 v12, v18, v144
	v_mul_f32_e32 v13, v19, v145
	v_mul_f32_e32 v6, v6, v146
	v_mul_f32_e32 v7, v7, v147
	v_cvt_pk_bf16_f32 v12, v12, v13
	v_cvt_pk_bf16_f32 v6, v6, v7
	s_nop 0
	v_cndmask_b32_e64 v7, v16, v12, s[2:3]
	v_cndmask_b32_e64 v13, v17, v6, s[2:3]
	ds_bpermute_b32 v7, v197, v7
	ds_bpermute_b32 v13, v197, v13
	s_waitcnt lgkmcnt(1)
	v_cndmask_b32_e64 v14, v12, v7, s[2:3]
	v_cndmask_b32_e64 v12, v7, v16, s[2:3]
	s_waitcnt lgkmcnt(0)
	v_cndmask_b32_e64 v15, v6, v13, s[2:3]
	v_cndmask_b32_e64 v13, v13, v17, s[2:3]
	global_store_dwordx4 v[4:5], v[12:15], off offset:192
	v_mul_f32_e32 v6, v8, v64
	v_mul_f32_e32 v7, v9, v64
	v_mul_f32_e32 v8, v10, v64
	v_mul_f32_e32 v9, v11, v64
	v_mul_f32_e32 v6, v6, v148
	v_mul_f32_e32 v7, v7, v149
	v_mul_f32_e32 v8, v8, v150
	v_mul_f32_e32 v9, v9, v151
	v_cvt_pk_bf16_f32 v10, v6, v7
	v_cvt_pk_bf16_f32 v11, v8, v9
	v_mul_f32_e32 v0, v0, v168
	v_mul_f32_e32 v1, v1, v169
	v_mul_f32_e32 v2, v2, v170
	v_mul_f32_e32 v3, v3, v171
	v_cvt_pk_bf16_f32 v0, v0, v1
	v_cvt_pk_bf16_f32 v1, v2, v3
	s_nop 0
	v_cndmask_b32_e64 v2, v10, v0, s[2:3]
	ds_bpermute_b32 v3, v197, v2
	v_cndmask_b32_e64 v2, v11, v1, s[2:3]
	ds_bpermute_b32 v6, v197, v2
	s_waitcnt lgkmcnt(1)
	v_cndmask_b32_e64 v2, v0, v3, s[2:3]
	v_cndmask_b32_e64 v0, v3, v10, s[2:3]
	s_waitcnt lgkmcnt(0)
	v_cndmask_b32_e64 v3, v1, v6, s[2:3]
	v_cndmask_b32_e64 v1, v6, v11, s[2:3]
	global_store_dwordx4 v[4:5], v[0:3], off offset:224

.LBB0_615:
	s_waitcnt lgkmcnt(0)
	s_barrier
	s_cmpk_gt_u32 s90, 0xff
	s_cbranch_scc1 .LBB0_546
	ds_read2st64_b32 v[68:69], v67 offset1:1
	ds_read2st64_b32 v[70:71], v67 offset0:2 offset1:3
	ds_read2st64_b32 v[72:73], v67 offset0:4 offset1:5
	ds_read2st64_b32 v[74:75], v67 offset0:6 offset1:7
	v_mov_b32_e32 v184, v48
	s_mov_b32 s0, 0xf800000
	s_mov_b32 s4, 0x3f4ccccd
	s_waitcnt lgkmcnt(0)
	v_mov_b32_e32 v65, v68
	v_pk_mul_f32 v[76:77], v[184:185], v[64:65]
	v_mov_b32_e32 v184, v49
	v_mov_b32_e32 v65, v69
	v_pk_mul_f32 v[68:69], v[184:185], v[64:65]
	v_mov_b32_e32 v184, v50
	v_mov_b32_e32 v65, v70
	v_sub_f32_e32 v49, v68, v69
	v_pk_mul_f32 v[68:69], v[184:185], v[64:65]
	v_mov_b32_e32 v184, v51
	v_mov_b32_e32 v65, v71
	v_sub_f32_e32 v50, v68, v69
	v_pk_mul_f32 v[68:69], v[184:185], v[64:65]
	v_mov_b32_e32 v184, v52
	v_mov_b32_e32 v65, v72
	v_sub_f32_e32 v66, v68, v69
	v_pk_mul_f32 v[68:69], v[184:185], v[64:65]
	v_mov_b32_e32 v184, v53
	v_mov_b32_e32 v65, v73
	v_pk_mul_f32 v[52:53], v[184:185], v[64:65]
	v_mov_b32_e32 v184, v54
	v_mov_b32_e32 v65, v74
	v_sub_f32_e32 v51, v68, v69
	v_pk_mul_f32 v[68:69], v[184:185], v[64:65]
	v_sub_f32_e32 v52, v52, v53
	v_sub_f32_e32 v53, v68, v69
	ds_read2st64_b32 v[68:69], v67 offset0:8 offset1:9
	v_mov_b32_e32 v184, v55
	v_mov_b32_e32 v65, v75
	ds_read2st64_b32 v[70:71], v67 offset0:10 offset1:11
	ds_read2st64_b32 v[72:73], v67 offset0:12 offset1:13
	ds_read2st64_b32 v[74:75], v67 offset0:14 offset1:15
	v_pk_mul_f32 v[54:55], v[184:185], v[64:65]
	v_mov_b32_e32 v184, v56
	s_waitcnt lgkmcnt(0)
	v_mov_b32_e32 v65, v68
	v_sub_f32_e32 v48, v76, v77
	v_pk_mul_f32 v[76:77], v[184:185], v[64:65]
	v_mov_b32_e32 v184, v57
	v_mov_b32_e32 v65, v69
	v_pk_mul_f32 v[56:57], v[184:185], v[64:65]
	v_mov_b32_e32 v184, v58
	v_mov_b32_e32 v65, v70
	v_pk_mul_f32 v[68:69], v[184:185], v[64:65]
	v_mov_b32_e32 v184, v59
	v_mov_b32_e32 v65, v71
	v_pk_mul_f32 v[58:59], v[184:185], v[64:65]
	v_mov_b32_e32 v184, v60
	v_mov_b32_e32 v65, v72
	v_sub_f32_e32 v56, v56, v57
	v_sub_f32_e32 v57, v68, v69
	v_pk_mul_f32 v[68:69], v[184:185], v[64:65]
	v_mov_b32_e32 v184, v61
	v_mov_b32_e32 v65, v73
	v_pk_mul_f32 v[60:61], v[184:185], v[64:65]
	v_mov_b32_e32 v184, v62
	v_mov_b32_e32 v65, v74
	v_sub_f32_e32 v58, v58, v59
	v_sub_f32_e32 v59, v68, v69
	v_pk_mul_f32 v[68:69], v[184:185], v[64:65]
	v_sub_f32_e32 v60, v60, v61
	v_sub_f32_e32 v61, v68, v69
	ds_read2st64_b32 v[68:69], v67 offset0:16 offset1:17
	v_mov_b32_e32 v184, v63
	v_mov_b32_e32 v65, v75
	ds_read2st64_b32 v[70:71], v67 offset0:18 offset1:19
	ds_read2st64_b32 v[72:73], v67 offset0:20 offset1:21
	ds_read2st64_b32 v[74:75], v67 offset0:22 offset1:23
	v_pk_mul_f32 v[62:63], v[184:185], v[64:65]
	v_mov_b32_e32 v184, v32
	s_waitcnt lgkmcnt(0)
	v_mov_b32_e32 v65, v68
	v_sub_f32_e32 v54, v54, v55
	v_sub_f32_e32 v55, v76, v77
	v_pk_mul_f32 v[76:77], v[184:185], v[64:65]
	v_mov_b32_e32 v184, v33
	v_mov_b32_e32 v65, v69
	v_pk_mul_f32 v[68:69], v[184:185], v[64:65]
	v_mov_b32_e32 v184, v34
	v_mov_b32_e32 v65, v70
	v_sub_f32_e32 v62, v62, v63
	v_sub_f32_e32 v63, v68, v69
	v_pk_mul_f32 v[68:69], v[184:185], v[64:65]
	v_mov_b32_e32 v184, v35
	v_mov_b32_e32 v65, v71
	v_sub_f32_e32 v34, v68, v69
	v_pk_mul_f32 v[68:69], v[184:185], v[64:65]
	v_mov_b32_e32 v184, v36
	v_mov_b32_e32 v65, v72
	v_pk_mul_f32 v[70:71], v[184:185], v[64:65]
	v_mov_b32_e32 v184, v37
	v_mov_b32_e32 v65, v73
	v_pk_mul_f32 v[36:37], v[184:185], v[64:65]
	v_mov_b32_e32 v184, v38
	v_mov_b32_e32 v65, v74
	v_sub_f32_e32 v35, v36, v37
	v_pk_mul_f32 v[36:37], v[184:185], v[64:65]
	v_mov_b32_e32 v184, v39
	v_mov_b32_e32 v65, v75
	v_pk_mul_f32 v[38:39], v[184:185], v[64:65]
	v_sub_f32_e32 v36, v36, v37
	v_sub_f32_e32 v37, v38, v39
	ds_read2st64_b32 v[38:39], v67 offset0:24 offset1:25
	v_sub_f32_e32 v33, v70, v71
	ds_read2st64_b32 v[70:71], v67 offset0:26 offset1:27
	ds_read2st64_b32 v[72:73], v67 offset0:28 offset1:29
	ds_read2st64_b32 v[74:75], v67 offset0:30 offset1:31
	v_mov_b32_e32 v184, v40
	v_sub_f32_e32 v32, v76, v77
	s_waitcnt lgkmcnt(0)
	v_mov_b32_e32 v65, v38
	v_pk_mul_f32 v[76:77], v[184:185], v[64:65]
	v_mov_b32_e32 v184, v41
	v_mov_b32_e32 v65, v39
	v_pk_mul_f32 v[40:41], v[184:185], v[64:65]
	v_mov_b32_e32 v184, v42
	v_mov_b32_e32 v65, v70
	v_sub_f32_e32 v38, v76, v77
	v_pk_mul_f32 v[76:77], v[184:185], v[64:65]
	v_mov_b32_e32 v184, v43
	v_mov_b32_e32 v65, v71
	v_pk_mul_f32 v[42:43], v[184:185], v[64:65]
	v_mov_b32_e32 v184, v44
	v_mov_b32_e32 v65, v72
	v_pk_mul_f32 v[70:71], v[184:185], v[64:65]
	v_mov_b32_e32 v184, v45
	v_mov_b32_e32 v65, v73
	v_pk_mul_f32 v[44:45], v[184:185], v[64:65]
	v_mov_b32_e32 v184, v46
	v_mov_b32_e32 v65, v74
	v_sub_f32_e32 v43, v42, v43
	v_sub_f32_e32 v42, v44, v45
	v_pk_mul_f32 v[44:45], v[184:185], v[64:65]
	v_mov_b32_e32 v184, v47
	v_mov_b32_e32 v65, v75
	v_pk_mul_f32 v[46:47], v[184:185], v[64:65]
	v_sub_f32_e32 v44, v44, v45
	v_sub_f32_e32 v45, v46, v47
	ds_read2st64_b32 v[46:47], v67 offset0:32 offset1:33
	v_sub_f32_e32 v39, v70, v71
	ds_read2st64_b32 v[70:71], v67 offset0:34 offset1:35
	ds_read2st64_b32 v[72:73], v67 offset0:36 offset1:37
	ds_read2st64_b32 v[74:75], v67 offset0:38 offset1:39
	v_mov_b32_e32 v184, v16
	v_sub_f32_e32 v40, v40, v41
	s_waitcnt lgkmcnt(0)
	v_mov_b32_e32 v65, v46
	v_sub_f32_e32 v41, v76, v77
	v_pk_mul_f32 v[76:77], v[184:185], v[64:65]
	v_mov_b32_e32 v184, v17
	v_mov_b32_e32 v65, v47
	v_pk_mul_f32 v[46:47], v[184:185], v[64:65]
	v_mov_b32_e32 v184, v18
	v_mov_b32_e32 v65, v70
	v_sub_f32_e32 v16, v76, v77
	v_pk_mul_f32 v[76:77], v[184:185], v[64:65]
	v_mov_b32_e32 v184, v19
	v_mov_b32_e32 v65, v71
	v_pk_mul_f32 v[70:71], v[184:185], v[64:65]
	v_mov_b32_e32 v184, v20
	v_mov_b32_e32 v65, v72
	v_sub_f32_e32 v46, v46, v47
	v_sub_f32_e32 v47, v70, v71
	v_pk_mul_f32 v[70:71], v[184:185], v[64:65]
	v_mov_b32_e32 v184, v21
	v_mov_b32_e32 v65, v73
	v_pk_mul_f32 v[20:21], v[184:185], v[64:65]
	v_mov_b32_e32 v184, v22
	v_mov_b32_e32 v65, v74
	v_sub_f32_e32 v19, v20, v21
	v_pk_mul_f32 v[20:21], v[184:185], v[64:65]
	v_mov_b32_e32 v184, v23
	v_mov_b32_e32 v65, v75
	v_pk_mul_f32 v[22:23], v[184:185], v[64:65]
	v_sub_f32_e32 v20, v20, v21
	v_sub_f32_e32 v21, v22, v23
	ds_read2st64_b32 v[22:23], v67 offset0:40 offset1:41
	v_sub_f32_e32 v17, v70, v71
	ds_read2st64_b32 v[70:71], v67 offset0:42 offset1:43
	ds_read2st64_b32 v[72:73], v67 offset0:44 offset1:45
	ds_read2st64_b32 v[74:75], v67 offset0:46 offset1:47
	v_mov_b32_e32 v184, v24
	v_sub_f32_e32 v18, v76, v77
	s_waitcnt lgkmcnt(0)
	v_mov_b32_e32 v65, v22
	v_pk_mul_f32 v[76:77], v[184:185], v[64:65]
	v_mov_b32_e32 v184, v25
	v_mov_b32_e32 v65, v23
	v_pk_mul_f32 v[24:25], v[184:185], v[64:65]
	v_mov_b32_e32 v184, v26
	v_mov_b32_e32 v65, v70
	v_sub_f32_e32 v22, v76, v77
	v_pk_mul_f32 v[76:77], v[184:185], v[64:65]
	v_mov_b32_e32 v184, v27
	v_mov_b32_e32 v65, v71
	v_pk_mul_f32 v[26:27], v[184:185], v[64:65]
	v_mov_b32_e32 v184, v28
	v_mov_b32_e32 v65, v72
	v_pk_mul_f32 v[70:71], v[184:185], v[64:65]
	v_mov_b32_e32 v184, v29
	v_mov_b32_e32 v65, v73
	v_pk_mul_f32 v[28:29], v[184:185], v[64:65]
	v_mov_b32_e32 v184, v30
	v_mov_b32_e32 v65, v74
	v_sub_f32_e32 v27, v26, v27
	v_sub_f32_e32 v26, v28, v29
	v_pk_mul_f32 v[28:29], v[184:185], v[64:65]
	v_mov_b32_e32 v184, v31
	v_mov_b32_e32 v65, v75
	v_pk_mul_f32 v[30:31], v[184:185], v[64:65]
	v_sub_f32_e32 v28, v28, v29
	v_sub_f32_e32 v29, v30, v31
	ds_read2st64_b32 v[30:31], v67 offset0:48 offset1:49
	v_sub_f32_e32 v24, v24, v25
	v_sub_f32_e32 v25, v76, v77
	v_sub_f32_e32 v23, v70, v71
	ds_read2st64_b32 v[70:71], v67 offset0:50 offset1:51
	ds_read2st64_b32 v[74:75], v67 offset0:52 offset1:53
	ds_read2st64_b32 v[76:77], v67 offset0:54 offset1:55
	v_mov_b32_e32 v184, v0
	s_waitcnt lgkmcnt(0)
	v_mov_b32_e32 v65, v30
	v_pk_mul_f32 v[72:73], v[184:185], v[64:65]
	v_mov_b32_e32 v184, v1
	v_mov_b32_e32 v65, v31
	v_pk_mul_f32 v[0:1], v[184:185], v[64:65]
	v_mov_b32_e32 v184, v2
	v_mov_b32_e32 v65, v70
	v_sub_f32_e32 v68, v68, v69
	v_sub_f32_e32 v69, v0, v1
	v_pk_mul_f32 v[0:1], v[184:185], v[64:65]
	v_mov_b32_e32 v184, v3
	v_mov_b32_e32 v65, v71
	v_sub_f32_e32 v70, v0, v1
	v_pk_mul_f32 v[0:1], v[184:185], v[64:65]
	v_mov_b32_e32 v184, v4
	v_mov_b32_e32 v65, v74
	v_sub_f32_e32 v30, v72, v73
	v_sub_f32_e32 v72, v0, v1
	v_pk_mul_f32 v[0:1], v[184:185], v[64:65]
	v_mov_b32_e32 v184, v5
	v_mov_b32_e32 v65, v75
	v_sub_f32_e32 v31, v0, v1
	v_pk_mul_f32 v[0:1], v[184:185], v[64:65]
	v_mov_b32_e32 v184, v6
	v_mov_b32_e32 v65, v76
	v_sub_f32_e32 v71, v0, v1
	v_pk_mul_f32 v[0:1], v[184:185], v[64:65]
	v_mov_b32_e32 v184, v7
	v_mov_b32_e32 v65, v77
	v_sub_f32_e32 v6, v0, v1
	v_pk_mul_f32 v[0:1], v[184:185], v[64:65]
	v_mov_b32_e32 v184, v8
	v_sub_f32_e32 v7, v0, v1
	ds_read2st64_b32 v[0:1], v67 offset0:56 offset1:57
	ds_read2st64_b32 v[2:3], v67 offset0:58 offset1:59
	ds_read2st64_b32 v[4:5], v67 offset0:60 offset1:61
	ds_read2st64_b32 v[74:75], v67 offset0:62 offset1:63
	v_mul_f32_e32 v67, v48, v48
	v_fmac_f32_e32 v67, v49, v49
	v_fmac_f32_e32 v67, v50, v50
	v_fmac_f32_e32 v67, v66, v66
	v_fmac_f32_e32 v67, v51, v51
	v_fmac_f32_e32 v67, v52, v52
	v_fmac_f32_e32 v67, v53, v53
	v_fmac_f32_e32 v67, v54, v54
	v_fmac_f32_e32 v67, v55, v55
	v_fmac_f32_e32 v67, v56, v56
	v_fmac_f32_e32 v67, v57, v57
	v_fmac_f32_e32 v67, v58, v58
	v_fmac_f32_e32 v67, v59, v59
	v_fmac_f32_e32 v67, v60, v60
	s_waitcnt lgkmcnt(0)
	v_mov_b32_e32 v65, v0
	v_fmac_f32_e32 v67, v61, v61
	v_pk_mul_f32 v[76:77], v[184:185], v[64:65]
	v_mov_b32_e32 v184, v9
	v_mov_b32_e32 v65, v1
	v_fmac_f32_e32 v67, v62, v62
	v_pk_mul_f32 v[0:1], v[184:185], v[64:65]
	v_mov_b32_e32 v184, v10
	v_mov_b32_e32 v65, v2
	v_fmac_f32_e32 v67, v32, v32
	v_sub_f32_e32 v9, v0, v1
	v_pk_mul_f32 v[0:1], v[184:185], v[64:65]
	v_mov_b32_e32 v184, v11
	v_mov_b32_e32 v65, v3
	v_fmac_f32_e32 v67, v63, v63
	v_sub_f32_e32 v10, v0, v1
	v_pk_mul_f32 v[0:1], v[184:185], v[64:65]
	v_fmac_f32_e32 v67, v34, v34
	v_sub_f32_e32 v11, v0, v1
	v_pk_mul_f32 v[0:1], v[186:187], v[4:5]
	v_pk_mul_f32 v[2:3], v[186:187], v[74:75]
	v_fmac_f32_e32 v67, v68, v68
	v_pk_fma_f32 v[0:1], v[12:13], v[64:65], v[0:1] op_sel_hi:[1,0,1] neg_lo:[0,0,1] neg_hi:[0,0,1]
	v_pk_fma_f32 v[2:3], v[14:15], v[64:65], v[2:3] op_sel_hi:[1,0,1] neg_lo:[0,0,1] neg_hi:[0,0,1]
	v_fmac_f32_e32 v67, v33, v33
	global_load_dwordx4 v[12:15], v[114:115], off
	global_load_dwordx4 v[80:83], v[114:115], off offset:32
	global_load_dwordx4 v[84:87], v[114:115], off offset:64
	global_load_dwordx4 v[88:91], v[114:115], off offset:96
	global_load_dwordx4 v[92:95], v[114:115], off offset:128
	global_load_dwordx4 v[96:99], v[114:115], off offset:160
	global_load_dwordx4 v[100:103], v[114:115], off offset:192
	global_load_dwordx4 v[104:107], v[114:115], off offset:224
	global_load_dwordx4 v[124:127], v[114:115], off offset:256
	global_load_dwordx4 v[128:131], v[114:115], off offset:288
	global_load_dwordx4 v[132:135], v[114:115], off offset:320
	global_load_dwordx4 v[136:139], v[114:115], off offset:352
	global_load_dwordx4 v[140:143], v[114:115], off offset:384
	global_load_dwordx4 v[144:147], v[114:115], off offset:416
	global_load_dwordx4 v[148:151], v[114:115], off offset:448
	global_load_dwordx4 v[168:171], v[114:115], off offset:480
	v_fmac_f32_e32 v67, v35, v35
	v_fmac_f32_e32 v67, v36, v36
	v_fmac_f32_e32 v67, v37, v37
	v_fmac_f32_e32 v67, v38, v38
	v_fmac_f32_e32 v67, v40, v40
	v_fmac_f32_e32 v67, v41, v41
	v_fmac_f32_e32 v67, v43, v43
	v_fmac_f32_e32 v67, v39, v39
	v_fmac_f32_e32 v67, v42, v42
	v_fmac_f32_e32 v67, v44, v44
	v_fmac_f32_e32 v67, v45, v45
	v_fmac_f32_e32 v67, v16, v16
	v_fmac_f32_e32 v67, v46, v46
	v_fmac_f32_e32 v67, v18, v18
	v_fmac_f32_e32 v67, v47, v47
	v_fmac_f32_e32 v67, v17, v17
	v_fmac_f32_e32 v67, v19, v19
	v_fmac_f32_e32 v67, v20, v20
	v_fmac_f32_e32 v67, v21, v21
	v_fmac_f32_e32 v67, v22, v22
	v_fmac_f32_e32 v67, v24, v24
	v_fmac_f32_e32 v67, v25, v25
	v_fmac_f32_e32 v67, v27, v27
	v_fmac_f32_e32 v67, v23, v23
	v_fmac_f32_e32 v67, v26, v26
	v_fmac_f32_e32 v67, v28, v28
	v_fmac_f32_e32 v67, v29, v29
	v_fmac_f32_e32 v67, v30, v30
	v_fmac_f32_e32 v67, v69, v69
	v_fmac_f32_e32 v67, v70, v70
	v_fmac_f32_e32 v67, v72, v72
	v_fmac_f32_e32 v67, v31, v31
	v_fmac_f32_e32 v67, v71, v71
	v_fmac_f32_e32 v67, v6, v6
	v_sub_f32_e32 v8, v76, v77
	v_fmac_f32_e32 v67, v7, v7
	v_fmac_f32_e32 v67, v8, v8
	v_fmac_f32_e32 v67, v9, v9
	v_fmac_f32_e32 v67, v10, v10
	v_pk_mul_f32 v[4:5], v[0:1], v[0:1]
	v_fmac_f32_e32 v67, v11, v11
	v_add_f32_e32 v4, v67, v4
	v_pk_mul_f32 v[64:65], v[2:3], v[2:3]
	v_add_f32_e32 v4, v4, v5
	v_add_f32_e32 v4, v4, v64
	v_add_f32_e32 v4, v4, v65
	ds_bpermute_b32 v5, v197, v4
	s_waitcnt lgkmcnt(0)
	v_add_f32_e32 v4, v4, v5
	v_fmamk_f32 v4, v4, 0x3c000000, v206
	v_mul_f32_e32 v5, 0x4f800000, v4
	v_cmp_gt_f32_e32 vcc, s0, v4
	s_nop 1
	v_cndmask_b32_e32 v4, v4, v5, vcc
	v_sqrt_f32_e32 v5, v4
	s_nop 0
	v_add_u32_e32 v64, -1, v5
	v_fma_f32 v65, -v64, v5, v4
	v_cmp_ge_f32_e64 s[0:1], 0, v65
	v_add_u32_e32 v65, 1, v5
	s_nop 0
	v_cndmask_b32_e64 v64, v5, v64, s[0:1]
	v_fma_f32 v5, -v65, v5, v4
	v_cmp_lt_f32_e64 s[0:1], 0, v5
	s_nop 1
	v_cndmask_b32_e64 v5, v64, v65, s[0:1]
	v_mul_f32_e32 v64, 0x37800000, v5
	v_cndmask_b32_e32 v5, v5, v64, vcc
	v_cmp_class_f32_e32 vcc, v4, v207
	s_nop 1
	v_cndmask_b32_e32 v4, v5, v4, vcc
	v_div_scale_f32 v5, s[0:1], v4, v4, s4
	v_rcp_f32_e32 v64, v5
	v_readlane_b32 s0, v249, 46
	v_readlane_b32 s1, v249, 47
	v_fma_f32 v65, -v5, v64, 1.0
	v_fmac_f32_e32 v64, v65, v64
	v_div_scale_f32 v65, vcc, s4, v4, s4
	v_mul_f32_e32 v67, v65, v64
	v_fma_f32 v73, -v5, v67, v65
	v_fmac_f32_e32 v67, v73, v64
	v_fma_f32 v5, -v5, v67, v65
	v_div_fmas_f32 v5, v5, v64, v67
	v_div_fixup_f32 v64, v5, v4, s4
	v_mul_f32_e32 v4, v48, v64
	v_mul_f32_e32 v5, v49, v64
	s_waitcnt vmcnt(0)
	v_mul_f32_e32 v4, v12, v4
	v_mul_f32_e32 v5, v13, v5
	v_cvt_pk_bf16_f32 v48, v4, v5
	v_mul_f32_e32 v4, v50, v64
	v_mul_f32_e32 v5, v66, v64
	v_mul_f32_e32 v4, v14, v4
	v_mul_f32_e32 v5, v15, v5
	v_cvt_pk_bf16_f32 v49, v4, v5
	v_mul_f32_e32 v50, v51, v64
	v_lshlrev_b64 v[4:5], 11, v[188:189]
	v_lshl_add_u64 v[4:5], s[0:1], 0, v[4:5]
	v_lshl_add_u64 v[4:5], v[4:5], 0, s[94:95]
	v_lshl_add_u64 v[4:5], v[4:5], 0, v[112:113]
	v_mul_f32_e32 v32, v32, v64
	v_mul_f32_e32 v34, v34, v64
	v_mul_f32_e32 v33, v33, v64
	v_mul_f32_e32 v35, v35, v64
	v_mul_f32_e32 v36, v36, v64
	v_mul_f32_e32 v37, v37, v64
	v_mul_f32_e32 v16, v16, v64
	v_mul_f32_e32 v18, v18, v64
	v_mul_f32_e32 v17, v17, v64
	v_mul_f32_e32 v19, v19, v64
	v_mul_f32_e32 v20, v20, v64
	v_mul_f32_e32 v21, v21, v64
	v_mul_f32_e32 v6, v6, v64
	v_mul_f32_e32 v7, v7, v64
	v_mul_f32_e32 v0, v0, v64
	v_mul_f32_e32 v1, v1, v64
	v_mul_f32_e32 v2, v2, v64
	v_mul_f32_e32 v3, v3, v64
	v_mul_f32_e32 v12, v80, v50
	v_mul_f32_e32 v50, v52, v64
	v_mul_f32_e32 v13, v81, v50
	v_cvt_pk_bf16_f32 v12, v12, v13
	v_mul_f32_e32 v13, v53, v64
	v_mul_f32_e32 v13, v82, v13
	v_mul_f32_e32 v14, v54, v64
	v_mul_f32_e32 v14, v83, v14
	v_cvt_pk_bf16_f32 v13, v13, v14
	v_cndmask_b32_e64 v14, v48, v12, s[2:3]
	ds_bpermute_b32 v15, v197, v14
	v_cndmask_b32_e64 v14, v49, v13, s[2:3]
	ds_bpermute_b32 v50, v197, v14
	s_waitcnt lgkmcnt(1)
	v_cndmask_b32_e64 v14, v12, v15, s[2:3]
	v_cndmask_b32_e64 v12, v15, v48, s[2:3]
	s_waitcnt lgkmcnt(0)
	v_cndmask_b32_e64 v15, v13, v50, s[2:3]
	v_cndmask_b32_e64 v13, v50, v49, s[2:3]
	global_store_dwordx4 v[4:5], v[12:15], off
	v_mul_f32_e32 v48, v55, v64
	v_mul_f32_e32 v50, v59, v64
	v_mul_f32_e32 v12, v48, v84
	v_mul_f32_e32 v48, v56, v64
	v_mul_f32_e32 v13, v48, v85
	v_cvt_pk_bf16_f32 v48, v12, v13
	v_mul_f32_e32 v12, v57, v64
	v_mul_f32_e32 v13, v58, v64
	v_mul_f32_e32 v12, v12, v86
	v_mul_f32_e32 v13, v13, v87
	v_cvt_pk_bf16_f32 v49, v12, v13
	v_mul_f32_e32 v12, v50, v88
	v_mul_f32_e32 v50, v60, v64
	v_mul_f32_e32 v13, v50, v89
	v_cvt_pk_bf16_f32 v12, v12, v13
	v_mul_f32_e32 v13, v61, v64
	v_mul_f32_e32 v13, v13, v90
	v_mul_f32_e32 v14, v62, v64
	v_mul_f32_e32 v14, v14, v91
	v_cvt_pk_bf16_f32 v13, v13, v14
	v_cndmask_b32_e64 v14, v48, v12, s[2:3]
	ds_bpermute_b32 v15, v197, v14
	v_cndmask_b32_e64 v14, v49, v13, s[2:3]
	ds_bpermute_b32 v50, v197, v14
	s_waitcnt lgkmcnt(1)
	v_cndmask_b32_e64 v14, v12, v15, s[2:3]
	v_cndmask_b32_e64 v12, v15, v48, s[2:3]
	s_waitcnt lgkmcnt(0)
	v_cndmask_b32_e64 v15, v13, v50, s[2:3]
	v_cndmask_b32_e64 v13, v50, v49, s[2:3]
	global_store_dwordx4 v[4:5], v[12:15], off offset:32
	v_mul_f32_e32 v48, v63, v64
	v_mul_f32_e32 v49, v68, v64
	v_mul_f32_e32 v12, v32, v92
	v_mul_f32_e32 v13, v48, v93
	v_mul_f32_e32 v14, v34, v94
	v_cvt_pk_bf16_f32 v32, v12, v13
	v_mul_f32_e32 v12, v49, v95
	v_cvt_pk_bf16_f32 v34, v14, v12
	v_mul_f32_e32 v12, v33, v96
	v_mul_f32_e32 v13, v35, v97
	v_mul_f32_e32 v14, v36, v98
	v_mul_f32_e32 v15, v37, v99
	v_cvt_pk_bf16_f32 v12, v12, v13
	v_cvt_pk_bf16_f32 v13, v14, v15
	v_mul_f32_e32 v35, v43, v64
	v_cndmask_b32_e64 v14, v32, v12, s[2:3]
	ds_bpermute_b32 v15, v197, v14
	v_cndmask_b32_e64 v14, v34, v13, s[2:3]
	ds_bpermute_b32 v33, v197, v14
	v_mul_f32_e32 v36, v44, v64
	v_mul_f32_e32 v37, v45, v64
	s_waitcnt lgkmcnt(1)
	v_cndmask_b32_e64 v14, v12, v15, s[2:3]
	v_cndmask_b32_e64 v12, v15, v32, s[2:3]
	s_waitcnt lgkmcnt(0)
	v_cndmask_b32_e64 v15, v13, v33, s[2:3]
	v_cndmask_b32_e64 v13, v33, v34, s[2:3]
	global_store_dwordx4 v[4:5], v[12:15], off offset:64
	v_mul_f32_e32 v32, v38, v64
	v_mul_f32_e32 v33, v40, v64
	v_mul_f32_e32 v34, v41, v64
	v_mul_f32_e32 v12, v32, v100
	v_mul_f32_e32 v13, v33, v101
	v_mul_f32_e32 v14, v34, v102
	v_mul_f32_e32 v15, v35, v103
	v_cvt_pk_bf16_f32 v32, v12, v13
	v_cvt_pk_bf16_f32 v33, v14, v15
	v_mul_f32_e32 v34, v39, v64
	v_mul_f32_e32 v35, v42, v64
	v_mul_f32_e32 v12, v34, v104
	v_mul_f32_e32 v13, v35, v105
	v_mul_f32_e32 v14, v36, v106
	v_mul_f32_e32 v15, v37, v107
	v_cvt_pk_bf16_f32 v12, v12, v13
	v_cvt_pk_bf16_f32 v13, v14, v15
	s_nop 0
	v_cndmask_b32_e64 v14, v32, v12, s[2:3]
	ds_bpermute_b32 v15, v197, v14
	v_cndmask_b32_e64 v14, v33, v13, s[2:3]
	ds_bpermute_b32 v34, v197, v14
	s_waitcnt lgkmcnt(1)
	v_cndmask_b32_e64 v14, v12, v15, s[2:3]
	v_cndmask_b32_e64 v12, v15, v32, s[2:3]
	s_waitcnt lgkmcnt(0)
	v_cndmask_b32_e64 v15, v13, v34, s[2:3]
	v_cndmask_b32_e64 v13, v34, v33, s[2:3]
	global_store_dwordx4 v[4:5], v[12:15], off offset:96
	v_mul_f32_e32 v32, v46, v64
	v_mul_f32_e32 v33, v47, v64
	v_mul_f32_e32 v12, v16, v124
	v_mul_f32_e32 v13, v32, v125
	v_mul_f32_e32 v14, v18, v126
	v_mul_f32_e32 v15, v33, v127
	v_cvt_pk_bf16_f32 v16, v12, v13
	v_cvt_pk_bf16_f32 v18, v14, v15
	v_mul_f32_e32 v12, v17, v128
	v_mul_f32_e32 v13, v19, v129
	v_mul_f32_e32 v14, v20, v130
	v_mul_f32_e32 v15, v21, v131
	v_cvt_pk_bf16_f32 v12, v12, v13
	v_cvt_pk_bf16_f32 v13, v14, v15
	v_mul_f32_e32 v19, v27, v64
	v_cndmask_b32_e64 v14, v16, v12, s[2:3]
	ds_bpermute_b32 v15, v197, v14
	v_cndmask_b32_e64 v14, v18, v13, s[2:3]
	ds_bpermute_b32 v17, v197, v14
	v_mul_f32_e32 v20, v28, v64
	v_mul_f32_e32 v21, v29, v64
	s_waitcnt lgkmcnt(1)
	v_cndmask_b32_e64 v14, v12, v15, s[2:3]
	v_cndmask_b32_e64 v12, v15, v16, s[2:3]
	s_waitcnt lgkmcnt(0)
	v_cndmask_b32_e64 v15, v13, v17, s[2:3]
	v_cndmask_b32_e64 v13, v17, v18, s[2:3]
	global_store_dwordx4 v[4:5], v[12:15], off offset:128
	v_mul_f32_e32 v16, v22, v64
	v_mul_f32_e32 v17, v24, v64
	v_mul_f32_e32 v18, v25, v64
	v_mul_f32_e32 v12, v16, v132
	v_mul_f32_e32 v13, v17, v133
	v_mul_f32_e32 v14, v18, v134
	v_mul_f32_e32 v15, v19, v135
	v_cvt_pk_bf16_f32 v16, v12, v13
	v_cvt_pk_bf16_f32 v17, v14, v15
	v_mul_f32_e32 v18, v23, v64
	v_mul_f32_e32 v19, v26, v64
	v_mul_f32_e32 v12, v18, v136
	v_mul_f32_e32 v13, v19, v137
	v_mul_f32_e32 v14, v20, v138
	v_mul_f32_e32 v15, v21, v139
	v_cvt_pk_bf16_f32 v12, v12, v13
	v_cvt_pk_bf16_f32 v13, v14, v15
	v_mul_f32_e32 v19, v72, v64
	v_cndmask_b32_e64 v14, v16, v12, s[2:3]
	ds_bpermute_b32 v15, v197, v14
	v_cndmask_b32_e64 v14, v17, v13, s[2:3]
	ds_bpermute_b32 v18, v197, v14
	s_waitcnt lgkmcnt(1)
	v_cndmask_b32_e64 v14, v12, v15, s[2:3]
	v_cndmask_b32_e64 v12, v15, v16, s[2:3]
	s_waitcnt lgkmcnt(0)
	v_cndmask_b32_e64 v15, v13, v18, s[2:3]
	v_cndmask_b32_e64 v13, v18, v17, s[2:3]
	global_store_dwordx4 v[4:5], v[12:15], off offset:160
	v_mul_f32_e32 v16, v30, v64
	v_mul_f32_e32 v17, v69, v64
	v_mul_f32_e32 v18, v70, v64
	v_mul_f32_e32 v12, v16, v140
	v_mul_f32_e32 v13, v17, v141
	v_mul_f32_e32 v14, v18, v142
	v_mul_f32_e32 v15, v19, v143
	v_cvt_pk_bf16_f32 v16, v12, v13
	v_cvt_pk_bf16_f32 v17, v14, v15
	v_mul_f32_e32 v18, v31, v64
	v_mul_f32_e32 v19, v71, v64
	v_mul_f32_e32 v12, v18, v144
	v_mul_f32_e32 v13, v19, v145
	v_mul_f32_e32 v6, v6, v146
	v_mul_f32_e32 v7, v7, v147
	v_cvt_pk_bf16_f32 v12, v12, v13
	v_cvt_pk_bf16_f32 v6, v6, v7
	s_nop 0
	v_cndmask_b32_e64 v7, v16, v12, s[2:3]
	v_cndmask_b32_e64 v13, v17, v6, s[2:3]
	ds_bpermute_b32 v7, v197, v7
	ds_bpermute_b32 v13, v197, v13
	s_waitcnt lgkmcnt(1)
	v_cndmask_b32_e64 v14, v12, v7, s[2:3]
	v_cndmask_b32_e64 v12, v7, v16, s[2:3]
	s_waitcnt lgkmcnt(0)
	v_cndmask_b32_e64 v15, v6, v13, s[2:3]
	v_cndmask_b32_e64 v13, v13, v17, s[2:3]
	global_store_dwordx4 v[4:5], v[12:15], off offset:192
	v_mul_f32_e32 v6, v8, v64
	v_mul_f32_e32 v7, v9, v64
	v_mul_f32_e32 v8, v10, v64
	v_mul_f32_e32 v9, v11, v64
	v_mul_f32_e32 v6, v6, v148
	v_mul_f32_e32 v7, v7, v149
	v_mul_f32_e32 v8, v8, v150
	v_mul_f32_e32 v9, v9, v151
	v_cvt_pk_bf16_f32 v10, v6, v7
	v_cvt_pk_bf16_f32 v11, v8, v9
	v_mul_f32_e32 v0, v0, v168
	v_mul_f32_e32 v1, v1, v169
	v_mul_f32_e32 v2, v2, v170
	v_mul_f32_e32 v3, v3, v171
	v_cvt_pk_bf16_f32 v0, v0, v1
	v_cvt_pk_bf16_f32 v1, v2, v3
	s_nop 0
	v_cndmask_b32_e64 v2, v10, v0, s[2:3]
	ds_bpermute_b32 v3, v197, v2
	v_cndmask_b32_e64 v2, v11, v1, s[2:3]
	ds_bpermute_b32 v6, v197, v2
	s_waitcnt lgkmcnt(1)
	v_cndmask_b32_e64 v2, v0, v3, s[2:3]
	v_cndmask_b32_e64 v0, v3, v10, s[2:3]
	s_waitcnt lgkmcnt(0)
	v_cndmask_b32_e64 v3, v1, v6, s[2:3]
	v_cndmask_b32_e64 v1, v6, v11, s[2:3]
	global_store_dwordx4 v[4:5], v[0:3], off offset:224
	s_branch .LBB0_546
